# attention latent items renumbered: head=item&7, q-group=(item>>3)&7 so the 8 q-groups of one (batch,head) share K/V in one XCD L2
# baseline (speedup 1.0000x reference)
.LBB0_187:
	s_ashr_i32 s16, s10, 6
	s_mov_b32 s13, 0
	s_andn2_b64 vcc, exec, s[4:5]
	s_mov_b32 s14, 0
	s_mov_b32 s12, 0
	s_mov_b32 s17, 0
	s_mov_b32 s3, s2
	s_mov_b32 s19, 0x9000
	s_movk_i32 s28, 0x1200
	s_mov_b32 s29, 0x800000
	s_movk_i32 s30, 0xffef
	s_mov_b32 s20, 0x3fb8aa3b
	s_mov_b32 s34, 0x3c800000
	s_cbranch_vccnz .LBB0_189
	s_lshr_b32 s4, s2, 3
	s_and_b32 s4, s4, 7
	s_lshl_b32 s5, s4, 2
	s_add_i32 s17, s16, s5
	s_max_i32 s6, s17, 4
	v_sub_u32_e64 v0, s5, 4 clamp
	s_add_i32 s6, s6, -4
	v_readfirstlane_b32 s14, v0
	v_sub_u32_e64 v0, s5, 1 clamp
	s_min_u32 s12, s6, 24
	s_max_u32 s6, s5, 4
	v_readfirstlane_b32 s5, v0
	s_min_u32 s5, s5, 24
	s_ashr_i32 s15, s2, 6
	s_sub_i32 s5, s5, s6
	s_add_i32 s13, s5, 12
	s_lshl_b32 s5, s15, 11
	s_lshl_b32 s4, s4, 8
	s_or_b32 s11, s5, s4
